# SSM-A chunk-state loop: all eight operand loads of an iteration issued at the top, counted waits before each 4-MFMA group (were load-wait-MFMA groups)
# speedup vs baseline: 1.0169x; 1.0043x over previous
.LBB0_623:
	v_lshl_add_u64 v[78:79], v[84:85], 0, s[8:9]
	v_add_co_u32_e32 v66, vcc, s66, v78
	s_nop 1
	v_addc_co_u32_e32 v67, vcc, 0, v79, vcc
	global_load_dwordx4 v[66:69], v[66:67], off
	v_add_co_u32_e32 v70, vcc, s67, v78
	s_nop 1
	v_addc_co_u32_e32 v71, vcc, 0, v79, vcc
	global_load_dwordx4 v[70:73], v[70:71], off
	v_add_co_u32_e32 v74, vcc, s68, v78
	s_nop 1
	v_addc_co_u32_e32 v75, vcc, 0, v79, vcc
	global_load_dwordx4 v[74:77], v[74:75], off
	v_add_co_u32_e32 v78, vcc, s69, v78
	s_nop 1
	v_addc_co_u32_e32 v79, vcc, 0, v79, vcc
	global_load_dwordx4 v[78:81], v[78:79], off
	v_lshl_add_u64 v[94:95], v[92:93], 0, s[8:9]
	v_add_co_u32_e32 v116, vcc, s70, v94
	s_nop 1
	v_addc_co_u32_e32 v117, vcc, 0, v95, vcc
	global_load_dwordx4 v[134:137], v[116:117], off
	v_add_co_u32_e32 v116, vcc, s71, v94
	s_nop 1
	v_addc_co_u32_e32 v117, vcc, 0, v95, vcc
	global_load_dwordx4 v[138:141], v[116:117], off
	v_add_co_u32_e32 v116, vcc, s72, v94
	s_nop 1
	v_addc_co_u32_e32 v117, vcc, 0, v95, vcc
	global_load_dwordx4 v[142:145], v[116:117], off
	v_lshl_add_u64 v[116:117], v[90:91], 0, s[8:9]
	global_load_dwordx4 v[146:149], v[116:117], off
	s_add_u32 s8, s8, 64
	s_addc_u32 s9, s9, 0
	ds_read_b128 v[116:119], v0
	ds_read_b128 v[120:123], v0 offset:16
	v_add_u32_e32 v0, 0x80, v0
	s_waitcnt vmcnt(4) lgkmcnt(0)
	v_and_b32_e32 v95, 0xffff0000, v66
	v_lshlrev_b32_e32 v94, 16, v66
	s_nop 0
	v_pk_mul_f32 v[94:95], v[116:117], v[94:95]
	s_nop 0
	v_cvt_pk_bf16_f32 v66, v94, v95
	v_and_b32_e32 v95, 0xffff0000, v70
	v_lshlrev_b32_e32 v94, 16, v70
	v_pk_mul_f32 v[94:95], v[116:117], v[94:95]
	s_nop 0
	v_cvt_pk_bf16_f32 v70, v94, v95
	v_and_b32_e32 v95, 0xffff0000, v74
	v_lshlrev_b32_e32 v94, 16, v74
	v_pk_mul_f32 v[94:95], v[116:117], v[94:95]
	s_nop 0
	v_cvt_pk_bf16_f32 v74, v94, v95
	v_and_b32_e32 v95, 0xffff0000, v78
	v_lshlrev_b32_e32 v94, 16, v78
	v_pk_mul_f32 v[94:95], v[116:117], v[94:95]
	s_nop 0
	v_cvt_pk_bf16_f32 v78, v94, v95
	v_and_b32_e32 v95, 0xffff0000, v67
	v_lshlrev_b32_e32 v94, 16, v67
	v_pk_mul_f32 v[94:95], v[118:119], v[94:95]
	s_nop 0
	v_cvt_pk_bf16_f32 v67, v94, v95
	v_and_b32_e32 v95, 0xffff0000, v71
	v_lshlrev_b32_e32 v94, 16, v71
	v_pk_mul_f32 v[94:95], v[118:119], v[94:95]
	s_nop 0
	v_cvt_pk_bf16_f32 v71, v94, v95
	v_and_b32_e32 v95, 0xffff0000, v75
	v_lshlrev_b32_e32 v94, 16, v75
	v_pk_mul_f32 v[94:95], v[118:119], v[94:95]
	s_nop 0
	v_cvt_pk_bf16_f32 v75, v94, v95
	v_and_b32_e32 v95, 0xffff0000, v79
	v_lshlrev_b32_e32 v94, 16, v79
	v_pk_mul_f32 v[94:95], v[118:119], v[94:95]
	s_nop 0
	v_cvt_pk_bf16_f32 v79, v94, v95
	v_and_b32_e32 v95, 0xffff0000, v68
	v_lshlrev_b32_e32 v94, 16, v68
	v_pk_mul_f32 v[94:95], v[120:121], v[94:95]
	s_nop 0
	v_cvt_pk_bf16_f32 v68, v94, v95
	v_and_b32_e32 v95, 0xffff0000, v72
	v_lshlrev_b32_e32 v94, 16, v72
	v_pk_mul_f32 v[94:95], v[120:121], v[94:95]
	s_nop 0
	v_cvt_pk_bf16_f32 v72, v94, v95
	v_and_b32_e32 v95, 0xffff0000, v76
	v_lshlrev_b32_e32 v94, 16, v76
	v_pk_mul_f32 v[94:95], v[120:121], v[94:95]
	s_nop 0
	v_cvt_pk_bf16_f32 v76, v94, v95
	v_and_b32_e32 v95, 0xffff0000, v80
	v_lshlrev_b32_e32 v94, 16, v80
	v_pk_mul_f32 v[94:95], v[120:121], v[94:95]
	s_nop 0
	v_cvt_pk_bf16_f32 v80, v94, v95
	v_and_b32_e32 v95, 0xffff0000, v69
	v_lshlrev_b32_e32 v94, 16, v69
	v_pk_mul_f32 v[94:95], v[122:123], v[94:95]
	s_nop 0
	v_cvt_pk_bf16_f32 v69, v94, v95
	v_and_b32_e32 v95, 0xffff0000, v73
	v_lshlrev_b32_e32 v94, 16, v73
	v_pk_mul_f32 v[94:95], v[122:123], v[94:95]
	s_nop 0
	v_cvt_pk_bf16_f32 v73, v94, v95
	v_and_b32_e32 v95, 0xffff0000, v77
	v_lshlrev_b32_e32 v94, 16, v77
	v_pk_mul_f32 v[94:95], v[122:123], v[94:95]
	s_nop 0
	v_cvt_pk_bf16_f32 v77, v94, v95
	v_and_b32_e32 v95, 0xffff0000, v81
	v_lshlrev_b32_e32 v94, 16, v81
	v_pk_mul_f32 v[94:95], v[122:123], v[94:95]
	s_nop 0
	v_cvt_pk_bf16_f32 v81, v94, v95
	s_nop 1
	s_waitcnt vmcnt(3)
	v_mfma_f32_16x16x32_bf16 v[62:65], v[66:69], v[134:137], v[62:65]
	v_mfma_f32_16x16x32_bf16 v[46:49], v[70:73], v[134:137], v[46:49]
	v_mfma_f32_16x16x32_bf16 v[30:33], v[74:77], v[134:137], v[30:33]
	v_mfma_f32_16x16x32_bf16 v[14:17], v[78:81], v[134:137], v[14:17]
	s_waitcnt vmcnt(2)
	v_mfma_f32_16x16x32_bf16 v[58:61], v[66:69], v[138:141], v[58:61]
	v_mfma_f32_16x16x32_bf16 v[42:45], v[70:73], v[138:141], v[42:45]
	v_mfma_f32_16x16x32_bf16 v[26:29], v[74:77], v[138:141], v[26:29]
	v_mfma_f32_16x16x32_bf16 v[10:13], v[78:81], v[138:141], v[10:13]
	s_waitcnt vmcnt(1)
	v_mfma_f32_16x16x32_bf16 v[54:57], v[66:69], v[142:145], v[54:57]
	v_mfma_f32_16x16x32_bf16 v[38:41], v[70:73], v[142:145], v[38:41]
	v_mfma_f32_16x16x32_bf16 v[22:25], v[74:77], v[142:145], v[22:25]
	v_mfma_f32_16x16x32_bf16 v[6:9], v[78:81], v[142:145], v[6:9]
	s_waitcnt vmcnt(0)
	v_mfma_f32_16x16x32_bf16 v[50:53], v[66:69], v[146:149], v[50:53]
	v_mfma_f32_16x16x32_bf16 v[34:37], v[70:73], v[146:149], v[34:37]
	v_mfma_f32_16x16x32_bf16 v[18:21], v[74:77], v[146:149], v[18:21]
	v_mfma_f32_16x16x32_bf16 v[2:5], v[78:81], v[146:149], v[2:5]
	s_cmpk_eq_i32 s8, 0x100
	s_cbranch_scc0 .LBB0_623
	v_or_b32_e32 v0, v114, v97
	v_lshl_add_u64 v[66:67], v[0:1], 2, v[82:83]
	v_add_u32_e32 v0, v114, v97
	global_store_dword v[66:67], v62, off
	v_lshl_add_u64 v[66:67], v[0:1], 2, v[82:83]
	v_add_u32_e32 v0, v114, v98
	global_store_dword v[66:67], v63, off offset:512
	global_store_dword v[66:67], v64, off offset:1024
	global_store_dword v[66:67], v65, off offset:1536
	global_store_dword v[66:67], v58, off offset:64
	v_lshl_add_u64 v[62:63], v[0:1], 2, v[82:83]
	v_add_u32_e32 v0, v114, v99
	global_store_dword v[62:63], v59, off offset:64
	v_lshl_add_u64 v[58:59], v[0:1], 2, v[82:83]
	v_add_u32_e32 v0, v114, v100
	v_lshl_add_u64 v[64:65], v[0:1], 2, v[82:83]
	v_or_b32_e32 v0, v114, v101
	global_store_dword v[58:59], v60, off offset:64
	global_store_dword v[64:65], v61, off offset:64
	global_store_dword v[66:67], v54, off offset:128
	global_store_dword v[62:63], v55, off offset:128
	global_store_dword v[58:59], v56, off offset:128
	global_store_dword v[64:65], v57, off offset:128
	global_store_dword v[66:67], v50, off offset:192
	global_store_dword v[62:63], v51, off offset:192
	global_store_dword v[58:59], v52, off offset:192
	global_store_dword v[64:65], v53, off offset:192
	v_lshl_add_u64 v[50:51], v[0:1], 2, v[82:83]
	v_or_b32_e32 v0, v114, v102
	global_store_dword v[50:51], v46, off
	v_lshl_add_u64 v[50:51], v[0:1], 2, v[82:83]
	v_or_b32_e32 v0, v114, v103
	global_store_dword v[50:51], v47, off
	v_lshl_add_u64 v[46:47], v[0:1], 2, v[82:83]
	v_or_b32_e32 v0, v114, v104
	global_store_dword v[46:47], v48, off
	v_lshl_add_u64 v[46:47], v[0:1], 2, v[82:83]
	v_add_u32_e32 v0, v114, v101
	global_store_dword v[46:47], v49, off
	v_lshl_add_u64 v[46:47], v[0:1], 2, v[82:83]
	v_add_u32_e32 v0, v114, v102
	v_lshl_add_u64 v[48:49], v[0:1], 2, v[82:83]
	v_add_u32_e32 v0, v114, v103
	global_store_dword v[46:47], v42, off offset:64
	global_store_dword v[48:49], v43, off offset:64
	v_lshl_add_u64 v[42:43], v[0:1], 2, v[82:83]
	v_add_u32_e32 v0, v114, v104
	v_lshl_add_u64 v[50:51], v[0:1], 2, v[82:83]
	v_or_b32_e32 v0, v114, v105
	global_store_dword v[42:43], v44, off offset:64
	global_store_dword v[50:51], v45, off offset:64
	global_store_dword v[46:47], v38, off offset:128
	global_store_dword v[48:49], v39, off offset:128
	global_store_dword v[42:43], v40, off offset:128
	global_store_dword v[50:51], v41, off offset:128
	global_store_dword v[46:47], v34, off offset:192
	global_store_dword v[48:49], v35, off offset:192
	global_store_dword v[42:43], v36, off offset:192
	global_store_dword v[50:51], v37, off offset:192
	v_lshl_add_u64 v[34:35], v[0:1], 2, v[82:83]
	v_or_b32_e32 v0, v114, v106
	global_store_dword v[34:35], v30, off
	v_lshl_add_u64 v[34:35], v[0:1], 2, v[82:83]
	v_or_b32_e32 v0, v114, v107
	global_store_dword v[34:35], v31, off
	v_lshl_add_u64 v[30:31], v[0:1], 2, v[82:83]
	v_or_b32_e32 v0, v114, v108
	global_store_dword v[30:31], v32, off
	v_lshl_add_u64 v[30:31], v[0:1], 2, v[82:83]
	v_add_u32_e32 v0, v114, v105
	global_store_dword v[30:31], v33, off
	v_lshl_add_u64 v[30:31], v[0:1], 2, v[82:83]
	v_add_u32_e32 v0, v114, v106
	v_lshl_add_u64 v[32:33], v[0:1], 2, v[82:83]
	v_add_u32_e32 v0, v114, v107
	global_store_dword v[30:31], v26, off offset:64
	global_store_dword v[32:33], v27, off offset:64
	v_lshl_add_u64 v[26:27], v[0:1], 2, v[82:83]
	v_add_u32_e32 v0, v114, v108
	v_lshl_add_u64 v[34:35], v[0:1], 2, v[82:83]
	v_or_b32_e32 v0, v114, v109
	global_store_dword v[26:27], v28, off offset:64
	global_store_dword v[34:35], v29, off offset:64
	global_store_dword v[30:31], v22, off offset:128
	global_store_dword v[32:33], v23, off offset:128
	global_store_dword v[26:27], v24, off offset:128
	global_store_dword v[34:35], v25, off offset:128
	global_store_dword v[30:31], v18, off offset:192
	global_store_dword v[32:33], v19, off offset:192
	global_store_dword v[26:27], v20, off offset:192
	global_store_dword v[34:35], v21, off offset:192
	v_lshl_add_u64 v[18:19], v[0:1], 2, v[82:83]
	v_or_b32_e32 v0, v114, v110
	global_store_dword v[18:19], v14, off
	v_lshl_add_u64 v[18:19], v[0:1], 2, v[82:83]
	v_or_b32_e32 v0, v114, v111
	global_store_dword v[18:19], v15, off
	v_lshl_add_u64 v[14:15], v[0:1], 2, v[82:83]
	v_or_b32_e32 v0, v114, v112
	global_store_dword v[14:15], v16, off
	v_lshl_add_u64 v[14:15], v[0:1], 2, v[82:83]
	v_add_u32_e32 v0, v114, v109
	global_store_dword v[14:15], v17, off
	v_lshl_add_u64 v[14:15], v[0:1], 2, v[82:83]
	v_add_u32_e32 v0, v114, v110
	v_lshl_add_u64 v[16:17], v[0:1], 2, v[82:83]
	v_add_u32_e32 v0, v114, v111
	global_store_dword v[14:15], v10, off offset:64
	global_store_dword v[16:17], v11, off offset:64
	v_lshl_add_u64 v[10:11], v[0:1], 2, v[82:83]
	v_add_u32_e32 v0, v114, v112
	v_lshl_add_u64 v[18:19], v[0:1], 2, v[82:83]
	s_mov_b32 s0, 64
	s_mov_b64 s[8:9], 0
	s_and_b64 vcc, exec, s[6:7]
	global_store_dword v[10:11], v12, off offset:64
	global_store_dword v[18:19], v13, off offset:64
	global_store_dword v[14:15], v6, off offset:128
	global_store_dword v[16:17], v7, off offset:128
	global_store_dword v[10:11], v8, off offset:128
	global_store_dword v[18:19], v9, off offset:128
	global_store_dword v[14:15], v2, off offset:192
	global_store_dword v[16:17], v3, off offset:192
	global_store_dword v[10:11], v4, off offset:192
	global_store_dword v[18:19], v5, off offset:192
	s_cbranch_vccz .LBB0_622
	s_movk_i32 s4, 0x2a0
	s_movk_i32 s0, 0x4c0
	s_movk_i32 s1, 0x90
	s_waitcnt lgkmcnt(0)
	s_barrier
	s_add_i32 s4, s44, s4
	s_cmp_ge_i32 s4, s0
	s_cbranch_scc0 .LBB0_627
	s_branch .LBB0_727
